# pool_prompt tile staging de-serialised: all 10 tile loads of a thread issued first, LDS writes behind counted waits (was load-wait-write per trip)
# speedup vs baseline: 1.0111x; 1.0087x over previous
; __device__ __forceinline__ int tid_opaque() { int t = threadIdx.x; asm volatile("" : "+v"(t)); return t; }
; __device__ __forceinline__ void pool_prompt(const Params& p, unsigned char* smem, int b, int rt, int g) {
;     const int tid = tid_opaque();
;     bf16_t* tile = (bf16_t*)smem;
;     const bf16_t* PROJ = (const bf16_t*)(p.ws + W_PROJ);
;     bf16_t* POOLED = (bf16_t*)(p.ws + W_XN);
;     const int r0 = b * TP + rt * 64;
; #pragma unroll
;     for (int v = tid; v < 79 * 64; v += 512) { const int k = v >> 6, cv = v & 63; int rr = r0 - 15 + k; rr = rr < 0 ? 0 : rr;
;         *(u32x4*)(tile + k * 512 + cv * 8) = __builtin_nontemporal_load((const u32x4*)(PROJ + (size_t)rr * NPROJ + C_U + g * 512 + cv * 8)); }
;     __syncthreads();
.LBB0_415:
	s_mul_hi_i32 s2, s46, 0x78787879
	s_lshr_b32 s3, s2, 31
	s_ashr_i32 s48, s2, 6
	s_add_i32 s48, s48, s3
	s_mul_i32 s2, s48, 0x88
	s_sub_i32 s2, s46, s2
	s_lshl_b32 s12, s2, 4
	v_mov_b32_e32 v2, v192
	s_mul_i32 s3, s48, 0x880
	s_andn2_b32 s12, s12, 63
	s_add_i32 s13, s12, s3
	v_cmp_gt_i32_e32 vcc, s39, v2
	s_and_saveexec_b64 s[4:5], vcc
	s_cbranch_execz .LBB0_418
	s_lshl_b32 s3, s47, 9
	s_add_i32 s2, s13, -15
	s_lshl_b32 s6, s3, 1
	s_add_u32 s10, s6, 0x7503000
	s_addc_u32 s11, s7, 0
	s_waitcnt vmcnt(0)
	v_ashrrev_i32_e32 v5, 6, v2
	v_lshlrev_b32_e32 v0, 4, v2
	v_and_b32_e32 v0, 0x3f0, v0
	v_lshlrev_b32_e32 v18, 10, v5
	v_add_u32_e32 v18, v18, v0
	v_add_u32_e32 v19, 0x10000, v18
	v_add_u32_e32 v16, s2, v5
	v_max_i32_e32 v17, 0, v16
	v_mov_b64_e32 v[12:13], s[88:89]
	s_nop 0
	v_mad_u64_u32 v[12:13], s[50:51], v17, s25, v[12:13]
	v_lshl_add_u64 v[12:13], v[12:13], 0, s[10:11]
	v_lshl_add_u64 v[12:13], v[12:13], 0, v[0:1]
	global_load_dwordx4 v[20:23], v[12:13], off offset:2048 nt
	v_add_u32_e32 v17, 8, v16
	v_max_i32_e32 v17, 0, v17
	v_mov_b64_e32 v[14:15], s[88:89]
	s_nop 0
	v_mad_u64_u32 v[14:15], s[50:51], v17, s25, v[14:15]
	v_lshl_add_u64 v[14:15], v[14:15], 0, s[10:11]
	v_lshl_add_u64 v[14:15], v[14:15], 0, v[0:1]
	global_load_dwordx4 v[24:27], v[14:15], off offset:2048 nt
	v_add_u32_e32 v17, 16, v16
	v_max_i32_e32 v17, 0, v17
	v_mov_b64_e32 v[12:13], s[88:89]
	s_nop 0
	v_mad_u64_u32 v[12:13], s[50:51], v17, s25, v[12:13]
	v_lshl_add_u64 v[12:13], v[12:13], 0, s[10:11]
	v_lshl_add_u64 v[12:13], v[12:13], 0, v[0:1]
	global_load_dwordx4 v[28:31], v[12:13], off offset:2048 nt
	v_add_u32_e32 v17, 24, v16
	v_max_i32_e32 v17, 0, v17
	v_mov_b64_e32 v[14:15], s[88:89]
	s_nop 0
	v_mad_u64_u32 v[14:15], s[50:51], v17, s25, v[14:15]
	v_lshl_add_u64 v[14:15], v[14:15], 0, s[10:11]
	v_lshl_add_u64 v[14:15], v[14:15], 0, v[0:1]
	global_load_dwordx4 v[32:35], v[14:15], off offset:2048 nt
	v_add_u32_e32 v17, 32, v16
	v_max_i32_e32 v17, 0, v17
	v_mov_b64_e32 v[12:13], s[88:89]
	s_nop 0
	v_mad_u64_u32 v[12:13], s[50:51], v17, s25, v[12:13]
	v_lshl_add_u64 v[12:13], v[12:13], 0, s[10:11]
	v_lshl_add_u64 v[12:13], v[12:13], 0, v[0:1]
	global_load_dwordx4 v[36:39], v[12:13], off offset:2048 nt
	v_add_u32_e32 v17, 40, v16
	v_max_i32_e32 v17, 0, v17
	v_mov_b64_e32 v[14:15], s[88:89]
	s_nop 0
	v_mad_u64_u32 v[14:15], s[50:51], v17, s25, v[14:15]
	v_lshl_add_u64 v[14:15], v[14:15], 0, s[10:11]
	v_lshl_add_u64 v[14:15], v[14:15], 0, v[0:1]
	global_load_dwordx4 v[40:43], v[14:15], off offset:2048 nt
	v_add_u32_e32 v17, 48, v16
	v_max_i32_e32 v17, 0, v17
	v_mov_b64_e32 v[12:13], s[88:89]
	s_nop 0
	v_mad_u64_u32 v[12:13], s[50:51], v17, s25, v[12:13]
	v_lshl_add_u64 v[12:13], v[12:13], 0, s[10:11]
	v_lshl_add_u64 v[12:13], v[12:13], 0, v[0:1]
	global_load_dwordx4 v[44:47], v[12:13], off offset:2048 nt
	v_add_u32_e32 v17, 56, v16
	v_max_i32_e32 v17, 0, v17
	v_mov_b64_e32 v[14:15], s[88:89]
	s_nop 0
	v_mad_u64_u32 v[14:15], s[50:51], v17, s25, v[14:15]
	v_lshl_add_u64 v[14:15], v[14:15], 0, s[10:11]
	v_lshl_add_u64 v[14:15], v[14:15], 0, v[0:1]
	global_load_dwordx4 v[48:51], v[14:15], off offset:2048 nt
	v_add_u32_e32 v17, 64, v16
	v_max_i32_e32 v17, 0, v17
	v_mov_b64_e32 v[12:13], s[88:89]
	s_nop 0
	v_mad_u64_u32 v[12:13], s[50:51], v17, s25, v[12:13]
	v_lshl_add_u64 v[12:13], v[12:13], 0, s[10:11]
	v_lshl_add_u64 v[12:13], v[12:13], 0, v[0:1]
	global_load_dwordx4 v[52:55], v[12:13], off offset:2048 nt
	v_add_u32_e32 v17, 72, v16
	v_max_i32_e32 v17, 0, v17
	v_mov_b64_e32 v[14:15], s[88:89]
	s_nop 0
	v_mad_u64_u32 v[14:15], s[50:51], v17, s25, v[14:15]
	v_lshl_add_u64 v[14:15], v[14:15], 0, s[10:11]
	v_lshl_add_u64 v[14:15], v[14:15], 0, v[0:1]
	global_load_dwordx4 v[56:59], v[14:15], off offset:2048 nt
	s_waitcnt vmcnt(9)
	ds_write_b128 v18, v[20:23]
	s_waitcnt vmcnt(8)
	ds_write_b128 v18, v[24:27] offset:8192
	s_waitcnt vmcnt(7)
	ds_write_b128 v18, v[28:31] offset:16384
	s_waitcnt vmcnt(6)
	ds_write_b128 v18, v[32:35] offset:24576
	s_waitcnt vmcnt(5)
	ds_write_b128 v18, v[36:39] offset:32768
	s_waitcnt vmcnt(4)
	ds_write_b128 v18, v[40:43] offset:40960
	s_waitcnt vmcnt(3)
	ds_write_b128 v18, v[44:47] offset:49152
	s_waitcnt vmcnt(2)
	ds_write_b128 v18, v[48:51] offset:57344
	s_waitcnt vmcnt(1)
	ds_write_b128 v19, v[52:55]
	s_waitcnt vmcnt(0)
	v_cmp_gt_u32_e32 vcc, 0x1c0, v2
	s_and_saveexec_b64 s[18:19], vcc
	ds_write_b128 v19, v[56:59] offset:8192
	s_or_b64 exec, exec, s[18:19]
